# S18 plus back-edge rotation in the attention unmasked loop: LDS ring-offset rotation moved ahead of the loop-back barrier (loop-edge edit)
# baseline (speedup 1.0000x reference)
; #define ATT_TOP(t) do { if ((t) + 2 < NT) ATT_LOADK((t) + 2); if ((t) + 1 < NT) ATT_LOADV((t) + 1); } while (0)
; #define ATT_BOT(t) do { if ((t) + 2 < NT) ATT_STOREK(k2); if ((t) + 1 < NT) ATT_STOREV(v1); __syncthreads(); \
;         { const int kk = k0; k0 = k1; k1 = k2; k2 = kk; const int vv = v0; v0 = v1; v1 = vv; } } while (0)
; #define ATT_RESC() do { if (__any(alpha_n < 1.f)) { _Pragma("unroll") for (int i = 0; i < 4; ++i) _Pragma("unroll") for (int r = 0; r < 16; ++r) o[i][r] *= alpha_n; } } while (0)
; __device__ __forceinline__ void unit(LAS unsigned char* lds, int b, int h, int qb, const bf16_t* Q, const bf16_t* Kn, const bf16_t* Kr, const bf16_t* VT, const bf16_t* proj, bf16_t* ymix, int wv) {
;     ...
;     for (; t + 1 < NT - 4; ++t) { ATT_TOP(t); ATT_QKN(k1); __builtin_amdgcn_sched_barrier(0); ATT_FUSED(t + 1, false); ATT_RESC(); ATT_BOT(t); }
.LBB0_617:
	v_pk_add_f32 v[110:111], v[220:221], 0 op_sel_hi:[1,0]
	s_add_i32 s8, s70, 0
	v_pk_add_f32 v[14:15], v[14:15], v[110:111]
	s_add_i32 s55, s55, 1
	v_pk_add_f32 v[12:13], v[12:13], v[14:15]
	s_add_i32 s58, s58, 64
	v_pk_add_f32 v[10:11], v[10:11], v[12:13]
	s_cmp_eq_u32 s63, s55
	v_pk_add_f32 v[10:11], v[98:99], v[10:11]
	s_nop 0
	v_pk_add_f32 v[10:11], v[96:97], v[10:11]
	s_nop 0
	v_pk_add_f32 v[10:11], v[112:113], v[10:11]
	s_nop 0
	v_pk_add_f32 v[10:11], v[100:101], v[10:11]
	s_nop 0
	v_pk_add_f32 v[10:11], v[114:115], v[10:11]
	s_nop 0
	v_pk_add_f32 v[10:11], v[102:103], v[10:11]
	s_nop 0
	v_pk_add_f32 v[10:11], v[116:117], v[10:11]
	s_nop 0
	v_pk_add_f32 v[10:11], v[104:105], v[10:11]
	s_nop 0
	v_pk_add_f32 v[10:11], v[118:119], v[10:11]
	s_nop 0
	v_pk_add_f32 v[10:11], v[106:107], v[10:11]
	s_nop 0
	v_pk_add_f32 v[10:11], v[120:121], v[10:11]
	s_nop 0
	v_pk_add_f32 v[10:11], v[108:109], v[10:11]
	s_nop 0
	v_add_f32_e32 v10, v10, v11
	v_fmac_f32_e32 v10, v228, v0
	v_add_u32_e32 v0, s61, v213
	v_add_u32_e32 v11, 0x2200, v0
	v_mov_b32_e32 v228, v10
	s_waitcnt vmcnt(1)
	ds_write2_b64 v0, v[2:3], v[4:5] offset1:1
	s_waitcnt vmcnt(0)
	ds_write2_b64 v11, v[6:7], v[8:9] offset1:1
	s_waitcnt lgkmcnt(0)
	s_cbranch_scc1 .Lrot_a
	s_mov_b32 s8, s60
	s_mov_b32 s60, s70
	s_mov_b32 s70, s72
	s_mov_b32 s9, s61
	s_mov_b32 s61, s71
.Lrot_a:
	s_barrier
	s_cbranch_scc1 .LBB0_620
	s_branch .LBB0_612

; #define ATT_TOP(t) do { if ((t) + 2 < NT) ATT_LOADK((t) + 2); if ((t) + 1 < NT) ATT_LOADV((t) + 1); } while (0)
; #define ATT_BOT(t) do { if ((t) + 2 < NT) ATT_STOREK(k2); if ((t) + 1 < NT) ATT_STOREV(v1); __syncthreads(); \
;         { const int kk = k0; k0 = k1; k1 = k2; k2 = kk; const int vv = v0; v0 = v1; v1 = vv; } } while (0)
; #define ATT_RESC() do { if (__any(alpha_n < 1.f)) { _Pragma("unroll") for (int i = 0; i < 4; ++i) _Pragma("unroll") for (int r = 0; r < 16; ++r) o[i][r] *= alpha_n; } } while (0)
; __device__ __forceinline__ void unit(LAS unsigned char* lds, int b, int h, int qb, const bf16_t* Q, const bf16_t* Kn, const bf16_t* Kr, const bf16_t* VT, const bf16_t* proj, bf16_t* ymix, int wv) {
;     ...
;     for (; t + 1 < NT - 4; ++t) { ATT_TOP(t); ATT_QKN(k1); __builtin_amdgcn_sched_barrier(0); ATT_FUSED(t + 1, false); ATT_RESC(); ATT_BOT(t); }
.LBB0_1182:
	v_pk_add_f32 v[110:111], v[220:221], 0 op_sel_hi:[1,0]
	s_add_i32 s6, s57, 0
	v_pk_add_f32 v[14:15], v[14:15], v[110:111]
	s_add_i32 s17, s17, 1
	v_pk_add_f32 v[12:13], v[12:13], v[14:15]
	s_add_i32 s36, s36, 64
	v_pk_add_f32 v[10:11], v[10:11], v[12:13]
	s_cmp_eq_u32 s41, s17
	v_pk_add_f32 v[10:11], v[98:99], v[10:11]
	s_nop 0
	v_pk_add_f32 v[10:11], v[96:97], v[10:11]
	s_nop 0
	v_pk_add_f32 v[10:11], v[112:113], v[10:11]
	s_nop 0
	v_pk_add_f32 v[10:11], v[100:101], v[10:11]
	s_nop 0
	v_pk_add_f32 v[10:11], v[114:115], v[10:11]
	s_nop 0
	v_pk_add_f32 v[10:11], v[102:103], v[10:11]
	s_nop 0
	v_pk_add_f32 v[10:11], v[116:117], v[10:11]
	s_nop 0
	v_pk_add_f32 v[10:11], v[104:105], v[10:11]
	s_nop 0
	v_pk_add_f32 v[10:11], v[118:119], v[10:11]
	s_nop 0
	v_pk_add_f32 v[10:11], v[106:107], v[10:11]
	s_nop 0
	v_pk_add_f32 v[10:11], v[120:121], v[10:11]
	s_nop 0
	v_pk_add_f32 v[10:11], v[108:109], v[10:11]
	s_nop 0
	v_add_f32_e32 v10, v10, v11
	v_fmac_f32_e32 v10, v228, v0
	v_add_u32_e32 v0, s39, v213
	v_add_u32_e32 v11, 0x2200, v0
	v_mov_b32_e32 v228, v10
	s_waitcnt vmcnt(1)
	ds_write2_b64 v0, v[2:3], v[4:5] offset1:1
	s_waitcnt vmcnt(0)
	ds_write2_b64 v11, v[6:7], v[8:9] offset1:1
	s_waitcnt lgkmcnt(0)
	s_cbranch_scc1 .Lrot_b
	s_mov_b32 s60, s38
	s_mov_b32 s38, s57
	s_mov_b32 s57, s59
	s_mov_b32 s59, s39
	s_mov_b32 s39, s58
